# hand-written prep_v (all 16 rows of a wave loaded up front, DPP row sums), run statically on workgroups 48..95 before the sp2 queue
# speedup vs baseline: 1.0257x; 1.0118x over previous
.Lpv_entry:
	s_sub_u32 s40, s63, 48
	s_cmp_lt_u32 s40, 48
	s_cbranch_scc0 .Ls5l_entry
	v_and_b32_e32 v74, 63, v206
	v_lshrrev_b32_e32 v75, 6, v206
	v_lshlrev_b32_e32 v72, 4, v74
	v_readfirstlane_b32 s40, v75
	s_sub_u32 s41, s63, 48
	s_lshl_b32 s42, s41, 7
	s_lshl_b32 s43, s40, 4
	s_add_u32 s42, s42, s43
	s_mul_i32 s42, s42, 0x2440
	s_add_u32 s42, s42, 0x3a25c40
	s_add_u32 s44, s96, s42
	s_addc_u32 s45, s97, 0
	v_readlane_b32 s46, v237, 29
	v_readlane_b32 s47, v237, 30
	s_lshl_b32 s42, s36, 10
	s_add_u32 s46, s46, s42
	s_addc_u32 s47, s47, 0
	global_load_dwordx4 v[68:71], v72, s[46:47]
	s_mul_i32 s42, s40, 8448
	global_load_dwordx4 v[4:7], v72, s[44:45]
	s_add_u32 s44, s44, 0x2440
	s_addc_u32 s45, s45, 0
	global_load_dwordx4 v[8:11], v72, s[44:45]
	s_add_u32 s44, s44, 0x2440
	s_addc_u32 s45, s45, 0
	global_load_dwordx4 v[12:15], v72, s[44:45]
	s_add_u32 s44, s44, 0x2440
	s_addc_u32 s45, s45, 0
	global_load_dwordx4 v[16:19], v72, s[44:45]
	s_add_u32 s44, s44, 0x2440
	s_addc_u32 s45, s45, 0
	global_load_dwordx4 v[20:23], v72, s[44:45]
	s_add_u32 s44, s44, 0x2440
	s_addc_u32 s45, s45, 0
	global_load_dwordx4 v[24:27], v72, s[44:45]
	s_add_u32 s44, s44, 0x2440
	s_addc_u32 s45, s45, 0
	global_load_dwordx4 v[28:31], v72, s[44:45]
	s_add_u32 s44, s44, 0x2440
	s_addc_u32 s45, s45, 0
	global_load_dwordx4 v[32:35], v72, s[44:45]
	s_add_u32 s44, s44, 0x2440
	s_addc_u32 s45, s45, 0
	global_load_dwordx4 v[36:39], v72, s[44:45]
	s_add_u32 s44, s44, 0x2440
	s_addc_u32 s45, s45, 0
	global_load_dwordx4 v[40:43], v72, s[44:45]
	s_add_u32 s44, s44, 0x2440
	s_addc_u32 s45, s45, 0
	global_load_dwordx4 v[44:47], v72, s[44:45]
	s_add_u32 s44, s44, 0x2440
	s_addc_u32 s45, s45, 0
	global_load_dwordx4 v[48:51], v72, s[44:45]
	s_add_u32 s44, s44, 0x2440
	s_addc_u32 s45, s45, 0
	global_load_dwordx4 v[52:55], v72, s[44:45]
	s_add_u32 s44, s44, 0x2440
	s_addc_u32 s45, s45, 0
	global_load_dwordx4 v[56:59], v72, s[44:45]
	s_add_u32 s44, s44, 0x2440
	s_addc_u32 s45, s45, 0
	global_load_dwordx4 v[60:63], v72, s[44:45]
	s_add_u32 s44, s44, 0x2440
	s_addc_u32 s45, s45, 0
	global_load_dwordx4 v[64:67], v72, s[44:45]
	s_mul_i32 s42, s40, 8448
	v_lshl_add_u32 v76, v74, 3, s42
	s_waitcnt vmcnt(0)
	s_mov_b32 s50, 0
.Lpv_rows:
	v_mul_f32_e32 v80, 0x3d372713, v4
	v_mul_f32_e32 v80, v4, v80
	v_fma_f32 v80, v4, v80, v4
	v_mul_f32_e32 v80, 0x3f4c422a, v80
	v_add_f32_e32 v80, v80, v80
	v_mul_f32_e32 v80, 0x3fb8aa3b, v80
	v_exp_f32_e32 v80, v80
	v_mul_f32_e32 v81, 0.5, v4
	v_add_f32_e32 v80, 1.0, v80
	v_div_scale_f32 v82, s[100:101], v80, v80, 2.0
	v_rcp_f32_e32 v83, v82
	s_nop 0
	v_fma_f32 v84, -v82, v83, 1.0
	v_fmac_f32_e32 v83, v84, v83
	v_div_scale_f32 v84, vcc, 2.0, v80, 2.0
	v_mul_f32_e32 v85, v84, v83
	v_fma_f32 v86, -v82, v85, v84
	v_fmac_f32_e32 v85, v86, v83
	v_fma_f32 v82, -v82, v85, v84
	v_div_fmas_f32 v82, v82, v83, v85
	v_div_fixup_f32 v80, v82, v80, 2.0
	v_sub_f32_e32 v80, 1.0, v80
	v_add_f32_e32 v80, 1.0, v80
	v_mul_f32_e32 v4, v81, v80
	v_mul_f32_e32 v80, 0x3d372713, v5
	v_mul_f32_e32 v80, v5, v80
	v_fma_f32 v80, v5, v80, v5
	v_mul_f32_e32 v80, 0x3f4c422a, v80
	v_add_f32_e32 v80, v80, v80
	v_mul_f32_e32 v80, 0x3fb8aa3b, v80
	v_exp_f32_e32 v80, v80
	v_mul_f32_e32 v81, 0.5, v5
	v_add_f32_e32 v80, 1.0, v80
	v_div_scale_f32 v82, s[100:101], v80, v80, 2.0
	v_rcp_f32_e32 v83, v82
	s_nop 0
	v_fma_f32 v84, -v82, v83, 1.0
	v_fmac_f32_e32 v83, v84, v83
	v_div_scale_f32 v84, vcc, 2.0, v80, 2.0
	v_mul_f32_e32 v85, v84, v83
	v_fma_f32 v86, -v82, v85, v84
	v_fmac_f32_e32 v85, v86, v83
	v_fma_f32 v82, -v82, v85, v84
	v_div_fmas_f32 v82, v82, v83, v85
	v_div_fixup_f32 v80, v82, v80, 2.0
	v_sub_f32_e32 v80, 1.0, v80
	v_add_f32_e32 v80, 1.0, v80
	v_mul_f32_e32 v5, v81, v80
	v_mul_f32_e32 v80, 0x3d372713, v6
	v_mul_f32_e32 v80, v6, v80
	v_fma_f32 v80, v6, v80, v6
	v_mul_f32_e32 v80, 0x3f4c422a, v80
	v_add_f32_e32 v80, v80, v80
	v_mul_f32_e32 v80, 0x3fb8aa3b, v80
	v_exp_f32_e32 v80, v80
	v_mul_f32_e32 v81, 0.5, v6
	v_add_f32_e32 v80, 1.0, v80
	v_div_scale_f32 v82, s[100:101], v80, v80, 2.0
	v_rcp_f32_e32 v83, v82
	s_nop 0
	v_fma_f32 v84, -v82, v83, 1.0
	v_fmac_f32_e32 v83, v84, v83
	v_div_scale_f32 v84, vcc, 2.0, v80, 2.0
	v_mul_f32_e32 v85, v84, v83
	v_fma_f32 v86, -v82, v85, v84
	v_fmac_f32_e32 v85, v86, v83
	v_fma_f32 v82, -v82, v85, v84
	v_div_fmas_f32 v82, v82, v83, v85
	v_div_fixup_f32 v80, v82, v80, 2.0
	v_sub_f32_e32 v80, 1.0, v80
	v_add_f32_e32 v80, 1.0, v80
	v_mul_f32_e32 v6, v81, v80
	v_mul_f32_e32 v80, 0x3d372713, v7
	v_mul_f32_e32 v80, v7, v80
	v_fma_f32 v80, v7, v80, v7
	v_mul_f32_e32 v80, 0x3f4c422a, v80
	v_add_f32_e32 v80, v80, v80
	v_mul_f32_e32 v80, 0x3fb8aa3b, v80
	v_exp_f32_e32 v80, v80
	v_mul_f32_e32 v81, 0.5, v7
	v_add_f32_e32 v80, 1.0, v80
	v_div_scale_f32 v82, s[100:101], v80, v80, 2.0
	v_rcp_f32_e32 v83, v82
	s_nop 0
	v_fma_f32 v84, -v82, v83, 1.0
	v_fmac_f32_e32 v83, v84, v83
	v_div_scale_f32 v84, vcc, 2.0, v80, 2.0
	v_mul_f32_e32 v85, v84, v83
	v_fma_f32 v86, -v82, v85, v84
	v_fmac_f32_e32 v85, v86, v83
	v_fma_f32 v82, -v82, v85, v84
	v_div_fmas_f32 v82, v82, v83, v85
	v_div_fixup_f32 v80, v82, v80, 2.0
	v_sub_f32_e32 v80, 1.0, v80
	v_add_f32_e32 v80, 1.0, v80
	v_mul_f32_e32 v7, v81, v80
	v_mul_f32_e32 v73, v4, v4
	v_fmac_f32_e32 v73, v5, v5
	v_fmac_f32_e32 v73, v6, v6
	v_fmac_f32_e32 v73, v7, v7
	s_nop 1
	v_add_f32_dpp v73, v73, v73 row_shr:1 row_mask:0xf bank_mask:0xf bound_ctrl:0
	s_nop 1
	v_add_f32_dpp v73, v73, v73 row_shr:2 row_mask:0xf bank_mask:0xf bound_ctrl:0
	s_nop 1
	v_add_f32_dpp v73, v73, v73 row_shr:4 row_mask:0xf bank_mask:0xf bound_ctrl:0
	s_nop 1
	v_add_f32_dpp v73, v73, v73 row_shr:8 row_mask:0xf bank_mask:0xf bound_ctrl:0
	s_nop 1
	v_readlane_b32 s42, v73, 15
	v_readlane_b32 s43, v73, 31
	v_readlane_b32 s48, v73, 47
	v_readlane_b32 s49, v73, 63
	v_mov_b32_e32 v74, s42
	v_add_f32_e32 v74, s43, v74
	v_add_f32_e32 v74, s48, v74
	v_add_f32_e32 v74, s49, v74
	v_mov_b32_e32 v75, 0x358637bd
	v_fmac_f32_e32 v75, 0x3b800000, v74
	v_rsq_f32_e32 v75, v75
	s_nop 0
	v_mul_f32_e32 v4, v4, v75
	v_mul_f32_e32 v4, v4, v68
	v_mul_f32_e32 v5, v5, v75
	v_mul_f32_e32 v5, v5, v69
	v_mul_f32_e32 v6, v6, v75
	v_mul_f32_e32 v6, v6, v70
	v_mul_f32_e32 v7, v7, v75
	v_mul_f32_e32 v7, v7, v71
	v_cvt_pk_bf16_f32 v88, v4, v5
	v_cvt_pk_bf16_f32 v89, v6, v7
	ds_write_b64 v76, v[88:89] offset:0
	v_mul_f32_e32 v80, 0x3d372713, v8
	v_mul_f32_e32 v80, v8, v80
	v_fma_f32 v80, v8, v80, v8
	v_mul_f32_e32 v80, 0x3f4c422a, v80
	v_add_f32_e32 v80, v80, v80
	v_mul_f32_e32 v80, 0x3fb8aa3b, v80
	v_exp_f32_e32 v80, v80
	v_mul_f32_e32 v81, 0.5, v8
	v_add_f32_e32 v80, 1.0, v80
	v_div_scale_f32 v82, s[100:101], v80, v80, 2.0
	v_rcp_f32_e32 v83, v82
	s_nop 0
	v_fma_f32 v84, -v82, v83, 1.0
	v_fmac_f32_e32 v83, v84, v83
	v_div_scale_f32 v84, vcc, 2.0, v80, 2.0
	v_mul_f32_e32 v85, v84, v83
	v_fma_f32 v86, -v82, v85, v84
	v_fmac_f32_e32 v85, v86, v83
	v_fma_f32 v82, -v82, v85, v84
	v_div_fmas_f32 v82, v82, v83, v85
	v_div_fixup_f32 v80, v82, v80, 2.0
	v_sub_f32_e32 v80, 1.0, v80
	v_add_f32_e32 v80, 1.0, v80
	v_mul_f32_e32 v8, v81, v80
	v_mul_f32_e32 v80, 0x3d372713, v9
	v_mul_f32_e32 v80, v9, v80
	v_fma_f32 v80, v9, v80, v9
	v_mul_f32_e32 v80, 0x3f4c422a, v80
	v_add_f32_e32 v80, v80, v80
	v_mul_f32_e32 v80, 0x3fb8aa3b, v80
	v_exp_f32_e32 v80, v80
	v_mul_f32_e32 v81, 0.5, v9
	v_add_f32_e32 v80, 1.0, v80
	v_div_scale_f32 v82, s[100:101], v80, v80, 2.0
	v_rcp_f32_e32 v83, v82
	s_nop 0
	v_fma_f32 v84, -v82, v83, 1.0
	v_fmac_f32_e32 v83, v84, v83
	v_div_scale_f32 v84, vcc, 2.0, v80, 2.0
	v_mul_f32_e32 v85, v84, v83
	v_fma_f32 v86, -v82, v85, v84
	v_fmac_f32_e32 v85, v86, v83
	v_fma_f32 v82, -v82, v85, v84
	v_div_fmas_f32 v82, v82, v83, v85
	v_div_fixup_f32 v80, v82, v80, 2.0
	v_sub_f32_e32 v80, 1.0, v80
	v_add_f32_e32 v80, 1.0, v80
	v_mul_f32_e32 v9, v81, v80
	v_mul_f32_e32 v80, 0x3d372713, v10
	v_mul_f32_e32 v80, v10, v80
	v_fma_f32 v80, v10, v80, v10
	v_mul_f32_e32 v80, 0x3f4c422a, v80
	v_add_f32_e32 v80, v80, v80
	v_mul_f32_e32 v80, 0x3fb8aa3b, v80
	v_exp_f32_e32 v80, v80
	v_mul_f32_e32 v81, 0.5, v10
	v_add_f32_e32 v80, 1.0, v80
	v_div_scale_f32 v82, s[100:101], v80, v80, 2.0
	v_rcp_f32_e32 v83, v82
	s_nop 0
	v_fma_f32 v84, -v82, v83, 1.0
	v_fmac_f32_e32 v83, v84, v83
	v_div_scale_f32 v84, vcc, 2.0, v80, 2.0
	v_mul_f32_e32 v85, v84, v83
	v_fma_f32 v86, -v82, v85, v84
	v_fmac_f32_e32 v85, v86, v83
	v_fma_f32 v82, -v82, v85, v84
	v_div_fmas_f32 v82, v82, v83, v85
	v_div_fixup_f32 v80, v82, v80, 2.0
	v_sub_f32_e32 v80, 1.0, v80
	v_add_f32_e32 v80, 1.0, v80
	v_mul_f32_e32 v10, v81, v80
	v_mul_f32_e32 v80, 0x3d372713, v11
	v_mul_f32_e32 v80, v11, v80
	v_fma_f32 v80, v11, v80, v11
	v_mul_f32_e32 v80, 0x3f4c422a, v80
	v_add_f32_e32 v80, v80, v80
	v_mul_f32_e32 v80, 0x3fb8aa3b, v80
	v_exp_f32_e32 v80, v80
	v_mul_f32_e32 v81, 0.5, v11
	v_add_f32_e32 v80, 1.0, v80
	v_div_scale_f32 v82, s[100:101], v80, v80, 2.0
	v_rcp_f32_e32 v83, v82
	s_nop 0
	v_fma_f32 v84, -v82, v83, 1.0
	v_fmac_f32_e32 v83, v84, v83
	v_div_scale_f32 v84, vcc, 2.0, v80, 2.0
	v_mul_f32_e32 v85, v84, v83
	v_fma_f32 v86, -v82, v85, v84
	v_fmac_f32_e32 v85, v86, v83
	v_fma_f32 v82, -v82, v85, v84
	v_div_fmas_f32 v82, v82, v83, v85
	v_div_fixup_f32 v80, v82, v80, 2.0
	v_sub_f32_e32 v80, 1.0, v80
	v_add_f32_e32 v80, 1.0, v80
	v_mul_f32_e32 v11, v81, v80
	v_mul_f32_e32 v73, v8, v8
	v_fmac_f32_e32 v73, v9, v9
	v_fmac_f32_e32 v73, v10, v10
	v_fmac_f32_e32 v73, v11, v11
	s_nop 1
	v_add_f32_dpp v73, v73, v73 row_shr:1 row_mask:0xf bank_mask:0xf bound_ctrl:0
	s_nop 1
	v_add_f32_dpp v73, v73, v73 row_shr:2 row_mask:0xf bank_mask:0xf bound_ctrl:0
	s_nop 1
	v_add_f32_dpp v73, v73, v73 row_shr:4 row_mask:0xf bank_mask:0xf bound_ctrl:0
	s_nop 1
	v_add_f32_dpp v73, v73, v73 row_shr:8 row_mask:0xf bank_mask:0xf bound_ctrl:0
	s_nop 1
	v_readlane_b32 s42, v73, 15
	v_readlane_b32 s43, v73, 31
	v_readlane_b32 s48, v73, 47
	v_readlane_b32 s49, v73, 63
	v_mov_b32_e32 v74, s42
	v_add_f32_e32 v74, s43, v74
	v_add_f32_e32 v74, s48, v74
	v_add_f32_e32 v74, s49, v74
	v_mov_b32_e32 v75, 0x358637bd
	v_fmac_f32_e32 v75, 0x3b800000, v74
	v_rsq_f32_e32 v75, v75
	s_nop 0
	v_mul_f32_e32 v8, v8, v75
	v_mul_f32_e32 v8, v8, v68
	v_mul_f32_e32 v9, v9, v75
	v_mul_f32_e32 v9, v9, v69
	v_mul_f32_e32 v10, v10, v75
	v_mul_f32_e32 v10, v10, v70
	v_mul_f32_e32 v11, v11, v75
	v_mul_f32_e32 v11, v11, v71
	v_cvt_pk_bf16_f32 v88, v8, v9
	v_cvt_pk_bf16_f32 v89, v10, v11
	ds_write_b64 v76, v[88:89] offset:528
	v_mul_f32_e32 v80, 0x3d372713, v12
	v_mul_f32_e32 v80, v12, v80
	v_fma_f32 v80, v12, v80, v12
	v_mul_f32_e32 v80, 0x3f4c422a, v80
	v_add_f32_e32 v80, v80, v80
	v_mul_f32_e32 v80, 0x3fb8aa3b, v80
	v_exp_f32_e32 v80, v80
	v_mul_f32_e32 v81, 0.5, v12
	v_add_f32_e32 v80, 1.0, v80
	v_div_scale_f32 v82, s[100:101], v80, v80, 2.0
	v_rcp_f32_e32 v83, v82
	s_nop 0
	v_fma_f32 v84, -v82, v83, 1.0
	v_fmac_f32_e32 v83, v84, v83
	v_div_scale_f32 v84, vcc, 2.0, v80, 2.0
	v_mul_f32_e32 v85, v84, v83
	v_fma_f32 v86, -v82, v85, v84
	v_fmac_f32_e32 v85, v86, v83
	v_fma_f32 v82, -v82, v85, v84
	v_div_fmas_f32 v82, v82, v83, v85
	v_div_fixup_f32 v80, v82, v80, 2.0
	v_sub_f32_e32 v80, 1.0, v80
	v_add_f32_e32 v80, 1.0, v80
	v_mul_f32_e32 v12, v81, v80
	v_mul_f32_e32 v80, 0x3d372713, v13
	v_mul_f32_e32 v80, v13, v80
	v_fma_f32 v80, v13, v80, v13
	v_mul_f32_e32 v80, 0x3f4c422a, v80
	v_add_f32_e32 v80, v80, v80
	v_mul_f32_e32 v80, 0x3fb8aa3b, v80
	v_exp_f32_e32 v80, v80
	v_mul_f32_e32 v81, 0.5, v13
	v_add_f32_e32 v80, 1.0, v80
	v_div_scale_f32 v82, s[100:101], v80, v80, 2.0
	v_rcp_f32_e32 v83, v82
	s_nop 0
	v_fma_f32 v84, -v82, v83, 1.0
	v_fmac_f32_e32 v83, v84, v83
	v_div_scale_f32 v84, vcc, 2.0, v80, 2.0
	v_mul_f32_e32 v85, v84, v83
	v_fma_f32 v86, -v82, v85, v84
	v_fmac_f32_e32 v85, v86, v83
	v_fma_f32 v82, -v82, v85, v84
	v_div_fmas_f32 v82, v82, v83, v85
	v_div_fixup_f32 v80, v82, v80, 2.0
	v_sub_f32_e32 v80, 1.0, v80
	v_add_f32_e32 v80, 1.0, v80
	v_mul_f32_e32 v13, v81, v80
	v_mul_f32_e32 v80, 0x3d372713, v14
	v_mul_f32_e32 v80, v14, v80
	v_fma_f32 v80, v14, v80, v14
	v_mul_f32_e32 v80, 0x3f4c422a, v80
	v_add_f32_e32 v80, v80, v80
	v_mul_f32_e32 v80, 0x3fb8aa3b, v80
	v_exp_f32_e32 v80, v80
	v_mul_f32_e32 v81, 0.5, v14
	v_add_f32_e32 v80, 1.0, v80
	v_div_scale_f32 v82, s[100:101], v80, v80, 2.0
	v_rcp_f32_e32 v83, v82
	s_nop 0
	v_fma_f32 v84, -v82, v83, 1.0
	v_fmac_f32_e32 v83, v84, v83
	v_div_scale_f32 v84, vcc, 2.0, v80, 2.0
	v_mul_f32_e32 v85, v84, v83
	v_fma_f32 v86, -v82, v85, v84
	v_fmac_f32_e32 v85, v86, v83
	v_fma_f32 v82, -v82, v85, v84
	v_div_fmas_f32 v82, v82, v83, v85
	v_div_fixup_f32 v80, v82, v80, 2.0
	v_sub_f32_e32 v80, 1.0, v80
	v_add_f32_e32 v80, 1.0, v80
	v_mul_f32_e32 v14, v81, v80
	v_mul_f32_e32 v80, 0x3d372713, v15
	v_mul_f32_e32 v80, v15, v80
	v_fma_f32 v80, v15, v80, v15
	v_mul_f32_e32 v80, 0x3f4c422a, v80
	v_add_f32_e32 v80, v80, v80
	v_mul_f32_e32 v80, 0x3fb8aa3b, v80
	v_exp_f32_e32 v80, v80
	v_mul_f32_e32 v81, 0.5, v15
	v_add_f32_e32 v80, 1.0, v80
	v_div_scale_f32 v82, s[100:101], v80, v80, 2.0
	v_rcp_f32_e32 v83, v82
	s_nop 0
	v_fma_f32 v84, -v82, v83, 1.0
	v_fmac_f32_e32 v83, v84, v83
	v_div_scale_f32 v84, vcc, 2.0, v80, 2.0
	v_mul_f32_e32 v85, v84, v83
	v_fma_f32 v86, -v82, v85, v84
	v_fmac_f32_e32 v85, v86, v83
	v_fma_f32 v82, -v82, v85, v84
	v_div_fmas_f32 v82, v82, v83, v85
	v_div_fixup_f32 v80, v82, v80, 2.0
	v_sub_f32_e32 v80, 1.0, v80
	v_add_f32_e32 v80, 1.0, v80
	v_mul_f32_e32 v15, v81, v80
	v_mul_f32_e32 v73, v12, v12
	v_fmac_f32_e32 v73, v13, v13
	v_fmac_f32_e32 v73, v14, v14
	v_fmac_f32_e32 v73, v15, v15
	s_nop 1
	v_add_f32_dpp v73, v73, v73 row_shr:1 row_mask:0xf bank_mask:0xf bound_ctrl:0
	s_nop 1
	v_add_f32_dpp v73, v73, v73 row_shr:2 row_mask:0xf bank_mask:0xf bound_ctrl:0
	s_nop 1
	v_add_f32_dpp v73, v73, v73 row_shr:4 row_mask:0xf bank_mask:0xf bound_ctrl:0
	s_nop 1
	v_add_f32_dpp v73, v73, v73 row_shr:8 row_mask:0xf bank_mask:0xf bound_ctrl:0
	s_nop 1
	v_readlane_b32 s42, v73, 15
	v_readlane_b32 s43, v73, 31
	v_readlane_b32 s48, v73, 47
	v_readlane_b32 s49, v73, 63
	v_mov_b32_e32 v74, s42
	v_add_f32_e32 v74, s43, v74
	v_add_f32_e32 v74, s48, v74
	v_add_f32_e32 v74, s49, v74
	v_mov_b32_e32 v75, 0x358637bd
	v_fmac_f32_e32 v75, 0x3b800000, v74
	v_rsq_f32_e32 v75, v75
	s_nop 0
	v_mul_f32_e32 v12, v12, v75
	v_mul_f32_e32 v12, v12, v68
	v_mul_f32_e32 v13, v13, v75
	v_mul_f32_e32 v13, v13, v69
	v_mul_f32_e32 v14, v14, v75
	v_mul_f32_e32 v14, v14, v70
	v_mul_f32_e32 v15, v15, v75
	v_mul_f32_e32 v15, v15, v71
	v_cvt_pk_bf16_f32 v88, v12, v13
	v_cvt_pk_bf16_f32 v89, v14, v15
	ds_write_b64 v76, v[88:89] offset:1056
	v_mul_f32_e32 v80, 0x3d372713, v16
	v_mul_f32_e32 v80, v16, v80
	v_fma_f32 v80, v16, v80, v16
	v_mul_f32_e32 v80, 0x3f4c422a, v80
	v_add_f32_e32 v80, v80, v80
	v_mul_f32_e32 v80, 0x3fb8aa3b, v80
	v_exp_f32_e32 v80, v80
	v_mul_f32_e32 v81, 0.5, v16
	v_add_f32_e32 v80, 1.0, v80
	v_div_scale_f32 v82, s[100:101], v80, v80, 2.0
	v_rcp_f32_e32 v83, v82
	s_nop 0
	v_fma_f32 v84, -v82, v83, 1.0
	v_fmac_f32_e32 v83, v84, v83
	v_div_scale_f32 v84, vcc, 2.0, v80, 2.0
	v_mul_f32_e32 v85, v84, v83
	v_fma_f32 v86, -v82, v85, v84
	v_fmac_f32_e32 v85, v86, v83
	v_fma_f32 v82, -v82, v85, v84
	v_div_fmas_f32 v82, v82, v83, v85
	v_div_fixup_f32 v80, v82, v80, 2.0
	v_sub_f32_e32 v80, 1.0, v80
	v_add_f32_e32 v80, 1.0, v80
	v_mul_f32_e32 v16, v81, v80
	v_mul_f32_e32 v80, 0x3d372713, v17
	v_mul_f32_e32 v80, v17, v80
	v_fma_f32 v80, v17, v80, v17
	v_mul_f32_e32 v80, 0x3f4c422a, v80
	v_add_f32_e32 v80, v80, v80
	v_mul_f32_e32 v80, 0x3fb8aa3b, v80
	v_exp_f32_e32 v80, v80
	v_mul_f32_e32 v81, 0.5, v17
	v_add_f32_e32 v80, 1.0, v80
	v_div_scale_f32 v82, s[100:101], v80, v80, 2.0
	v_rcp_f32_e32 v83, v82
	s_nop 0
	v_fma_f32 v84, -v82, v83, 1.0
	v_fmac_f32_e32 v83, v84, v83
	v_div_scale_f32 v84, vcc, 2.0, v80, 2.0
	v_mul_f32_e32 v85, v84, v83
	v_fma_f32 v86, -v82, v85, v84
	v_fmac_f32_e32 v85, v86, v83
	v_fma_f32 v82, -v82, v85, v84
	v_div_fmas_f32 v82, v82, v83, v85
	v_div_fixup_f32 v80, v82, v80, 2.0
	v_sub_f32_e32 v80, 1.0, v80
	v_add_f32_e32 v80, 1.0, v80
	v_mul_f32_e32 v17, v81, v80
	v_mul_f32_e32 v80, 0x3d372713, v18
	v_mul_f32_e32 v80, v18, v80
	v_fma_f32 v80, v18, v80, v18
	v_mul_f32_e32 v80, 0x3f4c422a, v80
	v_add_f32_e32 v80, v80, v80
	v_mul_f32_e32 v80, 0x3fb8aa3b, v80
	v_exp_f32_e32 v80, v80
	v_mul_f32_e32 v81, 0.5, v18
	v_add_f32_e32 v80, 1.0, v80
	v_div_scale_f32 v82, s[100:101], v80, v80, 2.0
	v_rcp_f32_e32 v83, v82
	s_nop 0
	v_fma_f32 v84, -v82, v83, 1.0
	v_fmac_f32_e32 v83, v84, v83
	v_div_scale_f32 v84, vcc, 2.0, v80, 2.0
	v_mul_f32_e32 v85, v84, v83
	v_fma_f32 v86, -v82, v85, v84
	v_fmac_f32_e32 v85, v86, v83
	v_fma_f32 v82, -v82, v85, v84
	v_div_fmas_f32 v82, v82, v83, v85
	v_div_fixup_f32 v80, v82, v80, 2.0
	v_sub_f32_e32 v80, 1.0, v80
	v_add_f32_e32 v80, 1.0, v80
	v_mul_f32_e32 v18, v81, v80
	v_mul_f32_e32 v80, 0x3d372713, v19
	v_mul_f32_e32 v80, v19, v80
	v_fma_f32 v80, v19, v80, v19
	v_mul_f32_e32 v80, 0x3f4c422a, v80
	v_add_f32_e32 v80, v80, v80
	v_mul_f32_e32 v80, 0x3fb8aa3b, v80
	v_exp_f32_e32 v80, v80
	v_mul_f32_e32 v81, 0.5, v19
	v_add_f32_e32 v80, 1.0, v80
	v_div_scale_f32 v82, s[100:101], v80, v80, 2.0
	v_rcp_f32_e32 v83, v82
	s_nop 0
	v_fma_f32 v84, -v82, v83, 1.0
	v_fmac_f32_e32 v83, v84, v83
	v_div_scale_f32 v84, vcc, 2.0, v80, 2.0
	v_mul_f32_e32 v85, v84, v83
	v_fma_f32 v86, -v82, v85, v84
	v_fmac_f32_e32 v85, v86, v83
	v_fma_f32 v82, -v82, v85, v84
	v_div_fmas_f32 v82, v82, v83, v85
	v_div_fixup_f32 v80, v82, v80, 2.0
	v_sub_f32_e32 v80, 1.0, v80
	v_add_f32_e32 v80, 1.0, v80
	v_mul_f32_e32 v19, v81, v80
	v_mul_f32_e32 v73, v16, v16
	v_fmac_f32_e32 v73, v17, v17
	v_fmac_f32_e32 v73, v18, v18
	v_fmac_f32_e32 v73, v19, v19
	s_nop 1
	v_add_f32_dpp v73, v73, v73 row_shr:1 row_mask:0xf bank_mask:0xf bound_ctrl:0
	s_nop 1
	v_add_f32_dpp v73, v73, v73 row_shr:2 row_mask:0xf bank_mask:0xf bound_ctrl:0
	s_nop 1
	v_add_f32_dpp v73, v73, v73 row_shr:4 row_mask:0xf bank_mask:0xf bound_ctrl:0
	s_nop 1
	v_add_f32_dpp v73, v73, v73 row_shr:8 row_mask:0xf bank_mask:0xf bound_ctrl:0
	s_nop 1
	v_readlane_b32 s42, v73, 15
	v_readlane_b32 s43, v73, 31
	v_readlane_b32 s48, v73, 47
	v_readlane_b32 s49, v73, 63
	v_mov_b32_e32 v74, s42
	v_add_f32_e32 v74, s43, v74
	v_add_f32_e32 v74, s48, v74
	v_add_f32_e32 v74, s49, v74
	v_mov_b32_e32 v75, 0x358637bd
	v_fmac_f32_e32 v75, 0x3b800000, v74
	v_rsq_f32_e32 v75, v75
	s_nop 0
	v_mul_f32_e32 v16, v16, v75
	v_mul_f32_e32 v16, v16, v68
	v_mul_f32_e32 v17, v17, v75
	v_mul_f32_e32 v17, v17, v69
	v_mul_f32_e32 v18, v18, v75
	v_mul_f32_e32 v18, v18, v70
	v_mul_f32_e32 v19, v19, v75
	v_mul_f32_e32 v19, v19, v71
	v_cvt_pk_bf16_f32 v88, v16, v17
	v_cvt_pk_bf16_f32 v89, v18, v19
	ds_write_b64 v76, v[88:89] offset:1584
	s_add_u32 s50, s50, 1
	s_cmp_eq_u32 s50, 4
	s_cbranch_scc1 .Lpv_rows_done
	v_add_u32_e32 v76, 2112, v76
	v_mov_b32_e32 v4, v20
	v_mov_b32_e32 v5, v21
	v_mov_b32_e32 v6, v22
	v_mov_b32_e32 v7, v23
	v_mov_b32_e32 v8, v24
	v_mov_b32_e32 v9, v25
	v_mov_b32_e32 v10, v26
	v_mov_b32_e32 v11, v27
	v_mov_b32_e32 v12, v28
	v_mov_b32_e32 v13, v29
	v_mov_b32_e32 v14, v30
	v_mov_b32_e32 v15, v31
	v_mov_b32_e32 v16, v32
	v_mov_b32_e32 v17, v33
	v_mov_b32_e32 v18, v34
	v_mov_b32_e32 v19, v35
	v_mov_b32_e32 v20, v36
	v_mov_b32_e32 v21, v37
	v_mov_b32_e32 v22, v38
	v_mov_b32_e32 v23, v39
	v_mov_b32_e32 v24, v40
	v_mov_b32_e32 v25, v41
	v_mov_b32_e32 v26, v42
	v_mov_b32_e32 v27, v43
	v_mov_b32_e32 v28, v44
	v_mov_b32_e32 v29, v45
	v_mov_b32_e32 v30, v46
	v_mov_b32_e32 v31, v47
	v_mov_b32_e32 v32, v48
	v_mov_b32_e32 v33, v49
	v_mov_b32_e32 v34, v50
	v_mov_b32_e32 v35, v51
	v_mov_b32_e32 v36, v52
	v_mov_b32_e32 v37, v53
	v_mov_b32_e32 v38, v54
	v_mov_b32_e32 v39, v55
	v_mov_b32_e32 v40, v56
	v_mov_b32_e32 v41, v57
	v_mov_b32_e32 v42, v58
	v_mov_b32_e32 v43, v59
	v_mov_b32_e32 v44, v60
	v_mov_b32_e32 v45, v61
	v_mov_b32_e32 v46, v62
	v_mov_b32_e32 v47, v63
	v_mov_b32_e32 v48, v64
	v_mov_b32_e32 v49, v65
	v_mov_b32_e32 v50, v66
	v_mov_b32_e32 v51, v67
	s_branch .Lpv_rows
.Lpv_rows_done:
	s_waitcnt lgkmcnt(0)
	s_barrier
	v_and_b32_e32 v74, 0xff, v206
	v_lshrrev_b32_e32 v75, 8, v206
	v_mul_u32_u24_e32 v77, 4224, v75
	v_lshl_add_u32 v77, v74, 1, v77
	s_lshl_b32 s42, s41, 16
	s_add_u32 s42, s42, 0xc784000
	s_add_u32 s44, s96, s42
	s_addc_u32 s45, s97, 0
	v_lshlrev_b32_e32 v78, 8, v74
	v_lshl_add_u32 v78, v75, 4, v78
	ds_read_u16 v88, v77 offset:0
	ds_read_u16 v89, v77 offset:1056
	ds_read_u16 v90, v77 offset:2112
	ds_read_u16 v91, v77 offset:3168
	ds_read_u16 v96, v77 offset:528
	ds_read_u16 v97, v77 offset:1584
	ds_read_u16 v98, v77 offset:2640
	ds_read_u16 v99, v77 offset:3696
	s_waitcnt lgkmcnt(0)
	v_lshl_or_b32 v88, v96, 16, v88
	v_lshl_or_b32 v89, v97, 16, v89
	v_lshl_or_b32 v90, v98, 16, v90
	v_lshl_or_b32 v91, v99, 16, v91
	global_store_dwordx4 v78, v[88:91], s[44:45] offset:0
	ds_read_u16 v92, v77 offset:8448
	ds_read_u16 v93, v77 offset:9504
	ds_read_u16 v94, v77 offset:10560
	ds_read_u16 v95, v77 offset:11616
	ds_read_u16 v96, v77 offset:8976
	ds_read_u16 v97, v77 offset:10032
	ds_read_u16 v98, v77 offset:11088
	ds_read_u16 v99, v77 offset:12144
	s_waitcnt lgkmcnt(0)
	v_lshl_or_b32 v92, v96, 16, v92
	v_lshl_or_b32 v93, v97, 16, v93
	v_lshl_or_b32 v94, v98, 16, v94
	v_lshl_or_b32 v95, v99, 16, v95
	global_store_dwordx4 v78, v[92:95], s[44:45] offset:32
	ds_read_u16 v88, v77 offset:16896
	ds_read_u16 v89, v77 offset:17952
	ds_read_u16 v90, v77 offset:19008
	ds_read_u16 v91, v77 offset:20064
	ds_read_u16 v96, v77 offset:17424
	ds_read_u16 v97, v77 offset:18480
	ds_read_u16 v98, v77 offset:19536
	ds_read_u16 v99, v77 offset:20592
	s_waitcnt lgkmcnt(0)
	v_lshl_or_b32 v88, v96, 16, v88
	v_lshl_or_b32 v89, v97, 16, v89
	v_lshl_or_b32 v90, v98, 16, v90
	v_lshl_or_b32 v91, v99, 16, v91
	global_store_dwordx4 v78, v[88:91], s[44:45] offset:64
	ds_read_u16 v92, v77 offset:25344
	ds_read_u16 v93, v77 offset:26400
	ds_read_u16 v94, v77 offset:27456
	ds_read_u16 v95, v77 offset:28512
	ds_read_u16 v96, v77 offset:25872
	ds_read_u16 v97, v77 offset:26928
	ds_read_u16 v98, v77 offset:27984
	ds_read_u16 v99, v77 offset:29040
	s_waitcnt lgkmcnt(0)
	v_lshl_or_b32 v92, v96, 16, v92
	v_lshl_or_b32 v93, v97, 16, v93
	v_lshl_or_b32 v94, v98, 16, v94
	v_lshl_or_b32 v95, v99, 16, v95
	global_store_dwordx4 v78, v[92:95], s[44:45] offset:96
	ds_read_u16 v88, v77 offset:33792
	ds_read_u16 v89, v77 offset:34848
	ds_read_u16 v90, v77 offset:35904
	ds_read_u16 v91, v77 offset:36960
	ds_read_u16 v96, v77 offset:34320
	ds_read_u16 v97, v77 offset:35376
	ds_read_u16 v98, v77 offset:36432
	ds_read_u16 v99, v77 offset:37488
	s_waitcnt lgkmcnt(0)
	v_lshl_or_b32 v88, v96, 16, v88
	v_lshl_or_b32 v89, v97, 16, v89
	v_lshl_or_b32 v90, v98, 16, v90
	v_lshl_or_b32 v91, v99, 16, v91
	global_store_dwordx4 v78, v[88:91], s[44:45] offset:128
	ds_read_u16 v92, v77 offset:42240
	ds_read_u16 v93, v77 offset:43296
	ds_read_u16 v94, v77 offset:44352
	ds_read_u16 v95, v77 offset:45408
	ds_read_u16 v96, v77 offset:42768
	ds_read_u16 v97, v77 offset:43824
	ds_read_u16 v98, v77 offset:44880
	ds_read_u16 v99, v77 offset:45936
	s_waitcnt lgkmcnt(0)
	v_lshl_or_b32 v92, v96, 16, v92
	v_lshl_or_b32 v93, v97, 16, v93
	v_lshl_or_b32 v94, v98, 16, v94
	v_lshl_or_b32 v95, v99, 16, v95
	global_store_dwordx4 v78, v[92:95], s[44:45] offset:160
	ds_read_u16 v88, v77 offset:50688
	ds_read_u16 v89, v77 offset:51744
	ds_read_u16 v90, v77 offset:52800
	ds_read_u16 v91, v77 offset:53856
	ds_read_u16 v96, v77 offset:51216
	ds_read_u16 v97, v77 offset:52272
	ds_read_u16 v98, v77 offset:53328
	ds_read_u16 v99, v77 offset:54384
	s_waitcnt lgkmcnt(0)
	v_lshl_or_b32 v88, v96, 16, v88
	v_lshl_or_b32 v89, v97, 16, v89
	v_lshl_or_b32 v90, v98, 16, v90
	v_lshl_or_b32 v91, v99, 16, v91
	global_store_dwordx4 v78, v[88:91], s[44:45] offset:192
	ds_read_u16 v92, v77 offset:59136
	ds_read_u16 v93, v77 offset:60192
	ds_read_u16 v94, v77 offset:61248
	ds_read_u16 v95, v77 offset:62304
	ds_read_u16 v96, v77 offset:59664
	ds_read_u16 v97, v77 offset:60720
	ds_read_u16 v98, v77 offset:61776
	ds_read_u16 v99, v77 offset:62832
	s_waitcnt lgkmcnt(0)
	v_lshl_or_b32 v92, v96, 16, v92
	v_lshl_or_b32 v93, v97, 16, v93
	v_lshl_or_b32 v94, v98, 16, v94
	v_lshl_or_b32 v95, v99, 16, v95
	global_store_dwordx4 v78, v[92:95], s[44:45] offset:224
	s_barrier
	s_branch .Ls5l_entry

.LBB0_642:
	s_or_b64 exec, exec, s[38:39]
	s_waitcnt lgkmcnt(0)
	s_barrier
	ds_read_b32 v0, v208
	s_movk_i32 s4, 0x32f
	s_waitcnt lgkmcnt(0)
	v_cmp_lt_i32_e32 vcc, s4, v0
	v_readfirstlane_b32 s60, v0
	s_nop 0
	s_add_u32 s99, s60, 0x630
	s_add_u32 s98, s60, 768
	s_cmp_lt_u32 s60, 48
	s_cselect_b32 s60, s99, s98
	s_cbranch_vccnz .LBB0_704
	v_readlane_b32 s44, v237, 9
	s_mul_i32 s40, s36, 0x5000
	s_lshl_b64 s[38:39], s[36:37], 12
	v_readlane_b32 s52, v237, 17
	s_mul_hi_i32 s35, s36, 0x5000
	v_readlane_b32 s53, v237, 18
	s_add_u32 s40, s52, s40
	v_readlane_b32 s54, v237, 19
	s_addc_u32 s41, s53, s35
	v_readlane_b32 s4, v235, 61
	v_readlane_b32 s55, v237, 20
	s_add_u32 s42, s54, s38
	v_readlane_b32 s5, v235, 62
	v_writelane_b32 v234, s16, 0
	s_addc_u32 s43, s55, s39
	s_lshl_b64 s[38:39], s[4:5], 2
	v_writelane_b32 v234, s17, 1
	s_mov_b32 s52, s18
	v_readlane_b32 s4, v237, 25
	v_readlane_b32 s8, v237, 29
	v_readlane_b32 s16, v237, 37
	v_readlane_b32 s17, v237, 38
	v_readlane_b32 s45, v237, 10
	v_readlane_b32 s6, v237, 27
	v_readlane_b32 s9, v237, 30
	v_readlane_b32 s16, v234, 0
	s_add_u32 s44, s8, s38
	s_mov_b32 s6, s52
	v_readlane_b32 s17, v234, 1
	s_addc_u32 s45, s9, s39
	v_readlane_b32 s46, v237, 11
	v_readlane_b32 s47, v237, 12
	v_readlane_b32 s48, v237, 13
	v_readlane_b32 s49, v237, 14
	v_readlane_b32 s50, v237, 15
	v_readlane_b32 s51, v237, 16
	v_readlane_b32 s56, v237, 21
	v_readlane_b32 s57, v237, 22
	v_readlane_b32 s58, v237, 23
	v_readlane_b32 s59, v237, 24
	v_readlane_b32 s5, v237, 26
	v_readlane_b32 s7, v237, 28
	v_readlane_b32 s10, v237, 31
	v_readlane_b32 s11, v237, 32
	v_readlane_b32 s12, v237, 33
	v_readlane_b32 s13, v237, 34
	v_readlane_b32 s14, v237, 35
	v_readlane_b32 s15, v237, 36
	v_readlane_b32 s18, v237, 39
	v_readlane_b32 s19, v237, 40
	s_branch .LBB0_646

.LBB0_645:
	s_or_b64 exec, exec, s[38:39]
	s_waitcnt lgkmcnt(0)
	s_barrier
	ds_read_b32 v0, v208
	s_movk_i32 s4, 0x32f
	s_waitcnt lgkmcnt(0)
	v_cmp_lt_i32_e32 vcc, s4, v0
	v_readfirstlane_b32 s60, v0
	s_nop 0
	s_add_u32 s99, s60, 0x630
	s_add_u32 s98, s60, 768
	s_cmp_lt_u32 s60, 48
	s_cselect_b32 s60, s99, s98
	s_cbranch_vccnz .LBB0_704

.LBB0_688:
	s_andn2_b64 vcc, exec, s[38:39]
	s_cbranch_vccnz .LBB0_692
.LBB0_692:
	v_readlane_b32 s4, v236, 39
	v_readlane_b32 s5, v236, 40
	s_barrier
	s_and_saveexec_b64 s[38:39], s[4:5]
	s_cbranch_execz .LBB0_645
	s_mov_b64 s[48:49], exec
	v_mbcnt_lo_u32_b32 v0, s48, 0
	v_mbcnt_hi_u32_b32 v0, s49, v0
	v_cmp_eq_u32_e32 vcc, 0, v0
	s_and_saveexec_b64 s[46:47], vcc
	s_cbranch_execz .LBB0_644
	s_bcnt1_i32_b64 s35, s[48:49]
	v_readlane_b32 s4, v235, 56
	v_mov_b32_e32 v1, s35
	v_readlane_b32 s5, v235, 57
	s_nop 4
	global_atomic_add v1, v2, v1, s[4:5] sc0
	s_branch .LBB0_644
